# GLA-G3: idle wave 7 touches the next item's cache lines (discarded loads) during Q/K staging so its loads hit the XCD L2
# speedup vs baseline: 1.0006x; 1.0006x over previous
; #define LAS __attribute__((address_space(3)))
; __device__ __forceinline__ f32x4 mfma16(bf16x8 a, bf16x8 b, f32x4 c) { return __builtin_amdgcn_mfma_f32_16x16x32_bf16(a, b, c, 0, 0, 0); }
; __device__ __forceinline__ void gla_prep(const PrepRegs& R, LAS unsigned char* lds, int wave, int fr, int fq) {
;     ...
;     for (int q = 0; q < 3; ++q) { const int tile = wave * 3 + q, mi = tile / 6, ni = tile % 6, dir = ni / 3;
;         f32x4 acc = (f32x4){0.f, 0.f, 0.f, 0.f};
; #pragma unroll
;         for (int kk = 0; kk < 2; ++kk) { const int t = mi * 16 + fr; bf16x8 tri;
; #pragma unroll
;             for (int e = 0; e < 8; ++e) { const int sidx = kk * 32 + fq * 8 + e; tri[e] = (dir ? (sidx >= t) : (sidx <= t)) ? (short)0x3F80 : (short)0; }
;             const bf16x8 bb = *(const LAS bf16x8*)(lds + GL_GT + (ni * 16 + fr) * 144 + kk * 64 + fq * 16);
;             acc = mfma16(tri, bb, acc); }
; #pragma unroll
;         for (int i = 0; i < 4; ++i) G[(dir * 64 + mi * 16 + fq * 4 + i) * 48 + (ni % 3) * 16 + fr] = acc[i]; }
; __global__ void __launch_bounds__(512, 2) hybrid_fwd(Params p_unused) {
;     ...
;           for (;;) {
;               __syncthreads();
;               if (t0) *(LAS unsigned*)(lds + QWORD_OFF) = nxt_it;
;               __syncthreads();
;               const int it = (int)*(LAS unsigned*)(lds + QWORD_OFF);
;               if (it >= nit) break;
;               if (t0) { const Params p = ldp(); nxt_it = atomicAdd((unsigned*)(p.ws + OFF_CTR) + 2 + l, 1u); }
;               const int b = it / (nch * 4), rem = it % (nch * 4);
;               if (PHM & 512) { const Params p = ldp(); gla_g3_item(wv, p, l, b, rem >> 2, rem & 3, lds); }
.Ltri_done_g3:
	s_nop 0
	v_or_b32_e32 v99, 33, v84
	ds_read_b128 v[48:51], v44
	ds_read_b128 v[52:55], v44 offset:64
	s_waitcnt lgkmcnt(1)
	v_mfma_f32_16x16x32_bf16 v[42:45], v[152:155], v[48:51], 0
	v_or_b32_e32 v41, 32, v84
	v_lshlrev_b32_e32 v40, 2, v96
	v_or_b32_e32 v107, 39, v84
	v_lshl_add_u32 v39, v81, 2, 0
	s_waitcnt lgkmcnt(0)
	v_mfma_f32_16x16x32_bf16 v[42:45], v[156:159], v[52:55], v[42:45]
	v_lshl_add_u32 v48, v94, 6, v93
	v_or_b32_e32 v48, v48, v40
	v_lshlrev_b32_e32 v49, 6, v95
	v_mul_lo_u32 v48, v48, s69
	v_add3_u32 v48, v39, v49, v48
	v_add_u32_e32 v49, 0x3400, v48
	v_or_b32_e32 v93, v88, v81
	s_nop 7
	ds_write2_b32 v49, v42, v43 offset0:128 offset1:176
	v_add_u32_e32 v42, 0x3600, v48
	v_lshl_or_b32 v43, v98, 4, v81
	ds_write2_b32 v42, v44, v45 offset0:96 offset1:144
	v_add_u32_e32 v42, 2, v98
	v_mad_u64_u32 v[52:53], s[4:5], v43, s55, v[38:39]
	v_cmp_gt_u32_e64 s[24:25], 5, v42
	ds_read_b128 v[48:51], v52
	ds_read_b128 v[52:55], v52 offset:64
	s_waitcnt lgkmcnt(1)
	v_mfma_f32_16x16x32_bf16 v[42:45], v[152:155], v[48:51], 0
	s_waitcnt lgkmcnt(0)
	v_mfma_f32_16x16x32_bf16 v[42:45], v[156:159], v[52:55], v[42:45]
	v_lshl_add_u32 v48, v89, 6, v88
	v_or_b32_e32 v48, v48, v40
	v_lshlrev_b32_e32 v49, 6, v91
	v_mul_lo_u32 v48, v48, s69
	v_add3_u32 v48, v39, v49, v48
	v_add_u32_e32 v49, 0x3400, v48
	v_or_b32_e32 v88, v75, v81
	s_nop 7
	ds_write2_b32 v49, v42, v43 offset0:128 offset1:176
	v_add_u32_e32 v42, 0x3600, v48
	v_lshl_or_b32 v43, v97, 4, v81
	ds_write2_b32 v42, v44, v45 offset0:96 offset1:144
	v_add_u32_e32 v42, 2, v97
	v_mad_u64_u32 v[52:53], s[4:5], v43, s55, v[38:39]
	v_cmp_gt_u32_e64 s[24:25], 5, v42
	ds_read_b128 v[48:51], v52
	ds_read_b128 v[52:55], v52 offset:64
	s_waitcnt lgkmcnt(1)
	v_mfma_f32_16x16x32_bf16 v[42:45], v[152:155], v[48:51], 0
	v_lshl_add_u32 v41, v77, 6, v75
	v_or_b32_e32 v41, v41, v40
	v_mul_lo_u32 v41, v41, s69
	s_waitcnt lgkmcnt(0)
	v_mfma_f32_16x16x32_bf16 v[42:45], v[156:159], v[52:55], v[42:45]
	v_lshlrev_b32_e32 v48, 6, v85
	v_add3_u32 v41, v39, v48, v41
	v_add_u32_e32 v48, 0x3400, v41
	v_add_u32_e32 v41, 0x3600, v41
	s_nop 7
	ds_write2_b32 v48, v42, v43 offset0:128 offset1:176
	ds_write2_b32 v41, v44, v45 offset0:96 offset1:144
	s_mov_b64 s[24:25], exec
	s_and_b64 exec, exec, s[10:11]
	v_mov_b32_e32 v226, 0x23ffc
	ds_write_b32 v226, v80
	s_mov_b64 exec, s[24:25]
	s_waitcnt lgkmcnt(0)
	s_barrier
	v_readfirstlane_b32 s101, v82
	s_cmp_lg_u32 s101, 7
	s_cbranch_scc1 .Lwarm_skip_g3
	v_mov_b32_e32 v226, 0x23ffc
	ds_read_b32 v226, v226
	s_waitcnt lgkmcnt(0)
	v_readfirstlane_b32 s101, v226
	s_cmp_ge_i32 s101, s1
	s_cbranch_scc1 .Lwarm_skip_g3
	v_mbcnt_lo_u32_b32 v227, -1, 0
	v_mbcnt_hi_u32_b32 v227, -1, v227
	v_mov_b32_e32 v226, s101
	v_mul_hi_u32 v234, v226, s29
	v_mul_lo_u32 v235, v234, s0
	v_sub_u32_e32 v235, v226, v235
	v_cmp_le_u32_e64 s[24:25], s0, v235
	v_subrev_u32_e32 v248, s0, v235
	v_add_u32_e32 v249, 1, v234
	v_cndmask_b32_e64 v235, v235, v248, s[24:25]
	v_cndmask_b32_e64 v234, v234, v249, s[24:25]
	v_cmp_le_u32_e64 s[24:25], s0, v235
	v_subrev_u32_e32 v248, s0, v235
	v_add_u32_e32 v249, 1, v234
	v_cndmask_b32_e64 v235, v235, v248, s[24:25]
	v_cndmask_b32_e64 v234, v234, v249, s[24:25]
	v_lshrrev_b32_e32 v248, 2, v235
	v_and_b32_e32 v249, 3, v235
	v_cmp_gt_u32_e64 s[24:25], 32, v248
	v_lshlrev_b32_e32 v250, 6, v248
	v_lshl_add_u32 v251, v234, 11, v250
	v_lshl_add_u32 v250, v234, 8, v250
	v_add_u32_e32 v250, 0x3800, v250
	v_cndmask_b32_e64 v250, v250, v251, s[24:25]
	v_add_u32_e32 v250, v250, v227
	v_mul_u32_u24_e32 v250, 0xc40, v250
	v_add_u32_e32 v250, 0x2c00000, v250
	v_mul_u32_u24_e32 v251, 0x60, v249
	v_add_u32_e32 v218, v250, v251
	v_lshl_add_u32 v219, v251, 1, v250
	v_writelane_b32 v255, s4, 60
	v_writelane_b32 v255, s5, 61
	s_load_dwordx2 s[4:5], s[90:91], 0xa8
	s_waitcnt lgkmcnt(0)
	global_load_dword v220, v250, s[4:5] offset:3072
	global_load_dword v220, v218, s[4:5] offset:1536
	global_load_dword v220, v218, s[4:5] offset:1628
	global_load_dword v220, v218, s[4:5] offset:1920
	global_load_dword v220, v218, s[4:5] offset:2012
	global_load_dword v220, v219, s[4:5] offset:2304
	global_load_dword v220, v219, s[4:5] offset:2432
	global_load_dword v220, v219, s[4:5] offset:2492
	v_lshl_add_u32 v221, v234, 2, v249
	v_mul_u32_u24_e32 v222, 0x48, v221
	v_add_u32_e32 v222, v222, v248
	v_mul_u32_u24_e32 v222, 0x2400, v222
	v_lshl_add_u32 v222, v227, 7, v222
	v_add_u32_e32 v222, 0x9920000, v222
	global_load_dword v220, v222, s[4:5]
	v_add_u32_e32 v223, 0x2000, v222
	global_load_dword v220, v223, s[4:5]
	v_add_u32_e32 v223, 0x51000, v222
	global_load_dword v220, v223, s[4:5]
	v_add_u32_e32 v223, 0x53000, v222
	global_load_dword v220, v223, s[4:5]
	v_lshl_add_u32 v224, v234, 10, v251
	v_add_u32_e32 v224, 0x280, v224
	v_add_u32_e32 v224, v224, v227
	v_lshlrev_b32_e32 v225, 12, v224
	v_lshl_add_u32 v225, v248, 7, v225
	v_add_u32_e32 v225, 0x6320000, v225
	v_lshlrev_b32_e32 v221, 9, v224
	v_lshl_add_u32 v221, v248, 7, v221
	v_add_u32_e32 v221, 0x831f000, v221
	v_cndmask_b32_e64 v225, v221, v225, s[24:25]
	global_load_dword v220, v225, s[4:5]
	v_mov_b32_e32 v221, 0x8000
	v_mov_b32_e32 v223, 0x40000
	v_cndmask_b32_e64 v221, v221, v223, s[24:25]
	v_add_u32_e32 v225, v225, v221
	global_load_dword v220, v225, s[4:5]
	v_readlane_b32 s4, v255, 60
	v_readlane_b32 s5, v255, 61
; #define LAS __attribute__((address_space(3)))
; __device__ __forceinline__ unsigned pk_bf16(float lo, float hi) { unsigned r; asm volatile("v_cvt_pk_bf16_f32 %0, %1, %2" : "=v"(r) : "v"(lo), "v"(hi)); return r; }
; __device__ __forceinline__ float bflo(unsigned w) { return __uint_as_float(w << 16); }
; __device__ __forceinline__ void gla_g3_item(int wv, const Params& p, int l, int b, int n, int h, LAS unsigned char* lds) {
;     ...
;     if (tid < 384) { const int t = t3;
;         float q1[4] = {bflo(q1w.x), bfhi(q1w.x), bflo(q1w.y), bfhi(q1w.y)}, q2[4] = {bflo(q2w.x), bfhi(q2w.x), bflo(q2w.y), bfhi(q2w.y)};
;         float k1[4] = {bflo(k1w.x), bfhi(k1w.x), bflo(k1w.y), bfhi(k1w.y)}, k2[4] = {bflo(k2w.x), bfhi(k2w.x), bflo(k2w.y), bfhi(k2w.y)};
;         { const float cn[4] = {ra[0], ra[2], rb[0], rb[2]}, sn[4] = {ra[1], ra[3], rb[1], rb[3]};
; #pragma unroll
;             for (int e = 0; e < 4; ++e) { float a1 = q1[e], a2 = q2[e]; q1[e] = a1 * cn[e] - a2 * sn[e]; q2[e] = a2 * cn[e] + a1 * sn[e];
;                 a1 = k1[e]; a2 = k2[e]; k1[e] = a1 * cn[e] - a2 * sn[e]; k2[e] = a2 * cn[e] + a1 * sn[e]; } }
; #pragma unroll
;         for (int dir = 0; dir < 2; ++dir) {
;             const f32x4 b1 = *(const LAS f32x4*)(G + (dir * 64 + t) * 48 + c1), b2 = *(const LAS f32x4*)(G + (dir * 64 + t) * 48 + c1 + 12);
;             float e1[4], e2[4], i1[4], i2[4];
; #pragma unroll
;             for (int e = 0; e < 4; ++e) { e1[e] = __expf(b1[e]); e2[e] = __expf(b2[e]); i1[e] = __expf(-b1[e]); i2[e] = __expf(-b2[e]); }
;             const float qs = 0.14433756729740643f;
;             u32x2 w;
;             w.x = pk_bf16(q1[0] * qs * e1[0], q1[1] * qs * e1[1]); w.y = pk_bf16(q1[2] * qs * e1[2], q1[3] * qs * e1[3]); *(LAS u32x2*)(lds + GL_Q + (dir * 64 + t) * 144 + c1 * 2) = w;
;             w.x = pk_bf16(q2[0] * qs * e2[0], q2[1] * qs * e2[1]); w.y = pk_bf16(q2[2] * qs * e2[2], q2[3] * qs * e2[3]); *(LAS u32x2*)(lds + GL_Q + (dir * 64 + t) * 144 + (c1 + 12) * 2) = w;
;             w.x = pk_bf16(k1[0] * i1[0], k1[1] * i1[1]); w.y = pk_bf16(k1[2] * i1[2], k1[3] * i1[3]); *(LAS u32x2*)(lds + GL_K + (dir * 64 + t) * 144 + c1 * 2) = w;
;             w.x = pk_bf16(k2[0] * i2[0], k2[1] * i2[1]); w.y = pk_bf16(k2[2] * i2[2], k2[3] * i2[3]); *(LAS u32x2*)(lds + GL_K + (dir * 64 + t) * 144 + (c1 + 12) * 2) = w; } }
.Lwarm_skip_g3:
	s_and_saveexec_b64 s[24:25], s[22:23]
	s_cbranch_execz .LBB0_993
	v_lshlrev_b32_e32 v43, 16, v72
	v_lshlrev_b32_e32 v42, 16, v70
	v_pk_mul_f32 v[44:45], v[34:35], v[42:43]
	v_pk_mul_f32 v[42:43], v[34:35], v[42:43] op_sel:[0,1] op_sel_hi:[1,0]
	v_sub_f32_e32 v41, v44, v45
	v_add_f32_e32 v48, v42, v43
	v_lshlrev_b32_e32 v43, 16, v68
	v_lshlrev_b32_e32 v42, 16, v66
	v_pk_mul_f32 v[44:45], v[34:35], v[42:43]
	v_pk_mul_f32 v[34:35], v[34:35], v[42:43] op_sel:[0,1] op_sel_hi:[1,0]
	v_sub_f32_e32 v44, v44, v45
	v_add_f32_e32 v45, v34, v35
	v_and_b32_e32 v35, 0xffff0000, v72
	v_and_b32_e32 v34, 0xffff0000, v70
	v_pk_mul_f32 v[42:43], v[36:37], v[34:35]
	v_pk_mul_f32 v[34:35], v[36:37], v[34:35] op_sel:[0,1] op_sel_hi:[1,0]
	v_sub_f32_e32 v49, v42, v43
	v_add_f32_e32 v50, v34, v35
	v_and_b32_e32 v35, 0xffff0000, v68
	v_and_b32_e32 v34, 0xffff0000, v66
	v_pk_mul_f32 v[42:43], v[36:37], v[34:35]
	v_pk_mul_f32 v[34:35], v[36:37], v[34:35] op_sel:[0,1] op_sel_hi:[1,0]
	v_sub_f32_e32 v42, v42, v43
	v_add_f32_e32 v43, v34, v35
	v_lshlrev_b32_e32 v35, 16, v73
	v_lshlrev_b32_e32 v34, 16, v71
	v_pk_mul_f32 v[36:37], v[30:31], v[34:35]
	v_pk_mul_f32 v[34:35], v[30:31], v[34:35] op_sel:[0,1] op_sel_hi:[1,0]
	v_sub_f32_e32 v51, v36, v37
	v_add_f32_e32 v52, v34, v35
	v_lshlrev_b32_e32 v35, 16, v69
	v_lshlrev_b32_e32 v34, 16, v67
	v_pk_mul_f32 v[36:37], v[30:31], v[34:35]
	v_pk_mul_f32 v[30:31], v[30:31], v[34:35] op_sel:[0,1] op_sel_hi:[1,0]
	v_sub_f32_e32 v53, v36, v37
	v_add_f32_e32 v54, v30, v31
	v_and_b32_e32 v31, 0xffff0000, v73
	v_and_b32_e32 v30, 0xffff0000, v71
	v_pk_mul_f32 v[34:35], v[32:33], v[30:31]
	v_pk_mul_f32 v[30:31], v[32:33], v[30:31] op_sel:[0,1] op_sel_hi:[1,0]
	v_sub_f32_e32 v36, v34, v35
	v_add_f32_e32 v55, v30, v31
	v_and_b32_e32 v31, 0xffff0000, v69
	v_and_b32_e32 v30, 0xffff0000, v67
	v_pk_mul_f32 v[34:35], v[32:33], v[30:31]
	v_pk_mul_f32 v[30:31], v[32:33], v[30:31] op_sel:[0,1] op_sel_hi:[1,0]
	v_lshlrev_b32_e32 v61, 1, v64
	v_add_f32_e32 v57, v30, v31
	v_lshlrev_b32_e32 v30, 2, v64
	v_mul_lo_u32 v31, v5, s69
	v_add3_u32 v64, 0, v30, v31
	ds_read_b128 v[30:33], v64 offset:13824
	v_sub_f32_e32 v56, v34, v35
	v_mul_f32_e32 v59, 0x3e13cd3a, v36
	ds_read_b128 v[34:37], v64 offset:13872
	v_mul_f32_e32 v41, 0x3e13cd3a, v41
	s_waitcnt lgkmcnt(1)
	v_mul_f32_e32 v66, 0x3fb8aa3b, v30
	v_mul_f32_e32 v30, 0xbfb8aa3b, v30
	v_exp_f32_e32 v68, v30
	s_waitcnt lgkmcnt(0)
	v_mul_f32_e32 v30, 0xbfb8aa3b, v34
	v_mul_f32_e32 v67, 0x3fb8aa3b, v34
	v_exp_f32_e32 v34, v30
	v_mul_f32_e32 v30, 0x3fb8aa3b, v31
	v_mul_f32_e32 v31, 0xbfb8aa3b, v31
	v_exp_f32_e32 v70, v31
	v_mul_f32_e32 v31, 0xbfb8aa3b, v35
	v_mul_f32_e32 v69, 0x3fb8aa3b, v35
	v_exp_f32_e32 v35, v31
	v_mul_f32_e32 v31, 0x3fb8aa3b, v32
	v_exp_f32_e32 v66, v66
	v_exp_f32_e32 v30, v30
	v_exp_f32_e32 v31, v31
	v_mul_f32_e32 v72, 0x3fb8aa3b, v33
	v_exp_f32_e32 v72, v72
	v_exp_f32_e32 v67, v67
	v_exp_f32_e32 v69, v69
	v_mul_f32_e32 v71, 0x3fb8aa3b, v36
	v_mul_f32_e32 v49, 0x3e13cd3a, v49
	v_mul_f32_e32 v51, 0x3e13cd3a, v51
	v_exp_f32_e32 v71, v71
	v_mul_f32_e32 v73, 0x3fb8aa3b, v37
	v_exp_f32_e32 v73, v73
	v_mul_f32_e32 v66, v41, v66
	v_mul_f32_e32 v30, v49, v30
	v_mul_f32_e32 v31, v51, v31
	v_mul_lo_u32 v5, v5, s55
	v_mul_f32_e32 v48, 0x3e13cd3a, v48
	v_mul_f32_e32 v50, 0x3e13cd3a, v50
	v_mul_f32_e32 v32, 0xbfb8aa3b, v32
	v_cvt_pk_bf16_f32 v30, v66, v30
	v_mul_f32_e32 v66, v59, v72
	v_cvt_pk_bf16_f32 v31, v31, v66
	v_add3_u32 v5, 0, v5, v61
	v_mul_f32_e32 v52, 0x3e13cd3a, v52
	v_exp_f32_e32 v32, v32
	v_mul_f32_e32 v33, 0xbfb8aa3b, v33
	ds_write_b64 v5, v[30:31] offset:39424
	v_mul_f32_e32 v30, v48, v67
	v_mul_f32_e32 v31, v50, v69
	v_mul_f32_e32 v55, 0x3e13cd3a, v55
	v_exp_f32_e32 v33, v33
	v_cvt_pk_bf16_f32 v30, v30, v31
	v_mul_f32_e32 v31, v52, v71
	v_mul_f32_e32 v36, 0xbfb8aa3b, v36
	v_mul_f32_e32 v61, v55, v73
	v_cvt_pk_bf16_f32 v31, v31, v61
	v_exp_f32_e32 v36, v36
	v_mul_f32_e32 v37, 0xbfb8aa3b, v37
	ds_write_b64 v5, v[30:31] offset:39448
	v_mul_f32_e32 v30, v44, v68
	v_mul_f32_e32 v31, v42, v70
	v_exp_f32_e32 v37, v37
	v_cvt_pk_bf16_f32 v30, v30, v31
	v_mul_f32_e32 v31, v53, v32
	v_mul_f32_e32 v32, v56, v33
	v_cvt_pk_bf16_f32 v31, v31, v32
	ds_write_b64 v5, v[30:31] offset:57856
	v_mul_f32_e32 v30, v45, v34
	v_mul_f32_e32 v31, v43, v35
	v_cvt_pk_bf16_f32 v30, v30, v31
	v_mul_f32_e32 v31, v54, v36
	v_mul_f32_e32 v32, v57, v37
	v_cvt_pk_bf16_f32 v31, v31, v32
	ds_write_b64 v5, v[30:31] offset:57880
	ds_read_b128 v[30:33], v64 offset:26112
	ds_read_b128 v[34:37], v64 offset:26160
	s_waitcnt lgkmcnt(1)
	v_mul_f32_e32 v61, 0x3fb8aa3b, v30
	v_mul_f32_e32 v30, 0xbfb8aa3b, v30
	v_exp_f32_e32 v66, v30
	s_waitcnt lgkmcnt(0)
	v_mul_f32_e32 v30, 0xbfb8aa3b, v34
	v_mul_f32_e32 v64, 0x3fb8aa3b, v34
	v_exp_f32_e32 v34, v30
	v_mul_f32_e32 v30, 0x3fb8aa3b, v31
	v_mul_f32_e32 v31, 0xbfb8aa3b, v31
	v_exp_f32_e32 v68, v31
	v_mul_f32_e32 v31, 0xbfb8aa3b, v35
	v_mul_f32_e32 v67, 0x3fb8aa3b, v35
	v_exp_f32_e32 v35, v31
	v_mul_f32_e32 v31, 0x3fb8aa3b, v32
	v_exp_f32_e32 v61, v61
	v_exp_f32_e32 v30, v30
	v_exp_f32_e32 v31, v31
	v_mul_f32_e32 v70, 0x3fb8aa3b, v33
	v_exp_f32_e32 v70, v70
	v_exp_f32_e32 v64, v64
	v_exp_f32_e32 v67, v67
	v_mul_f32_e32 v69, 0x3fb8aa3b, v36
	v_exp_f32_e32 v69, v69
	v_mul_f32_e32 v71, 0x3fb8aa3b, v37
	v_exp_f32_e32 v71, v71
	v_mul_f32_e32 v33, 0xbfb8aa3b, v33
	v_mul_f32_e32 v41, v41, v61
	v_mul_f32_e32 v30, v49, v30
	v_mul_f32_e32 v31, v51, v31
	v_mul_f32_e32 v32, 0xbfb8aa3b, v32
	v_exp_f32_e32 v33, v33
	v_cvt_pk_bf16_f32 v30, v41, v30
	v_mul_f32_e32 v41, v59, v70
	v_cvt_pk_bf16_f32 v31, v31, v41
	v_exp_f32_e32 v32, v32
	v_mul_f32_e32 v37, 0xbfb8aa3b, v37
	ds_write_b64 v5, v[30:31] offset:48640
	v_mul_f32_e32 v30, v48, v64
	v_mul_f32_e32 v31, v50, v67
	v_mul_f32_e32 v36, 0xbfb8aa3b, v36
	v_exp_f32_e32 v37, v37
	v_cvt_pk_bf16_f32 v30, v30, v31
	v_mul_f32_e32 v31, v52, v69
	v_exp_f32_e32 v36, v36
	v_mul_f32_e32 v48, v55, v71
	v_cvt_pk_bf16_f32 v31, v31, v48
	v_add_u32_e32 v41, 0x2400, v5
	ds_write_b64 v5, v[30:31] offset:48664
	v_mul_f32_e32 v5, v44, v66
	v_mul_f32_e32 v30, v42, v68
	v_mul_f32_e32 v31, v56, v33
	v_cvt_pk_bf16_f32 v30, v5, v30
	v_mul_f32_e32 v5, v53, v32
	v_cvt_pk_bf16_f32 v31, v5, v31
	ds_write_b64 v41, v[30:31] offset:57856
	v_mul_f32_e32 v5, v45, v34
	v_mul_f32_e32 v30, v43, v35
	v_mul_f32_e32 v31, v57, v37
	v_cvt_pk_bf16_f32 v30, v5, v30
	v_mul_f32_e32 v5, v54, v36
	v_cvt_pk_bf16_f32 v31, v5, v31
	ds_write_b64 v41, v[30:31] offset:57880
